# no s_setprio in GEMM K-loops; final-epilogue ssp reloads issued together instead of one-at-a-time
# baseline (speedup 1.0000x reference)
;     __device__ __forceinline__ void operator()(const f32x4 (&acc)[2][2][4][2], const Unit& u, int wr, int wc, int fr, int fq) const {
;     ...
;         __builtin_amdgcn_s_barrier(); asm volatile("" ::: "memory");
;         float rs[2][4];
;         { f32x4 p[2][4];
; #pragma unroll
;           for (int ai = 0; ai < 2; ++ai)
; #pragma unroll
;             for (int m = 0; m < 4; ++m) p[ai][m] = *(const volatile f32x4*)(ssp + (size_t)(row0 + ai * HALF + m * 16) * 16 + 4 * fq);
; #pragma unroll
;           for (int ai = 0; ai < 2; ++ai)
; #pragma unroll
;             for (int m = 0; m < 4; ++m) { float s = (p[ai][m][0] + p[ai][m][1]) + (p[ai][m][2] + p[ai][m][3]); s += __shfl_xor(s, 16); s += __shfl_xor(s, 32); rs[ai][m] = __builtin_amdgcn_rsqf(s * (1.0f / D_MODEL) + RMS_EPS); } }
; #pragma unroll
;         for (int ai = 0; ai < 2; ++ai)
; #pragma unroll
;             for (int m = 0; m < 4; ++m) { const size_t off = (size_t)(row0 + ai * HALF + m * 16) * D_MODEL + col0; const float r = rs[ai][m];
; #pragma unroll
;                 for (int bj = 0; bj < 2; ++bj) { *(f32x4*)(out + off + bj * HALF) = o[ai][m][bj][0] * r * gv[bj][0]; *(f32x4*)(out + off + bj * HALF + 4) = o[ai][m][bj][1] * r * gv[bj][1]; } }
.LBB0_1210:
	s_barrier
	v_lshl_add_u64 v[86:87], v[160:161], 0, v[186:187]
	flat_load_dwordx4 v[208:211], v[86:87] sc0 sc1
	v_lshl_add_u64 v[86:87], v[160:161], 0, v[188:189]
	flat_load_dwordx4 v[186:189], v[86:87] sc0 sc1
	v_lshl_add_u64 v[86:87], v[160:161], 0, v[190:191]
	flat_load_dwordx4 v[212:215], v[86:87] sc0 sc1
	v_lshl_add_u64 v[86:87], v[160:161], 0, v[192:193]
	flat_load_dwordx4 v[190:193], v[86:87] sc0 sc1
	v_lshl_add_u64 v[86:87], v[160:161], 0, v[194:195]
	v_lshl_add_u64 v[80:81], v[160:161], 0, v[80:81]
	flat_load_dwordx4 v[216:219], v[86:87] sc0 sc1
	flat_load_dwordx4 v[220:223], v[80:81] sc0 sc1
	v_lshl_add_u64 v[80:81], v[160:161], 0, v[82:83]
	v_lshl_add_u64 v[84:85], v[160:161], 0, v[84:85]
	flat_load_dwordx4 v[80:83], v[80:81] sc0 sc1
	s_and_b64 vcc, exec, s[4:5]
	flat_load_dwordx4 v[84:87], v[84:85] sc0 sc1
	s_waitcnt vmcnt(0)
	s_mov_b64 s[2:3], -1
	s_waitcnt lgkmcnt(0)
	v_mov_b32_e32 v194, v209
	v_mov_b32_e32 v195, v210
	v_mov_b32_e32 v209, v211
	v_mov_b32_e32 v210, v187
	v_mov_b32_e32 v211, v188
	v_mov_b32_e32 v187, v189
	v_mov_b32_e32 v188, v213
	v_mov_b32_e32 v189, v214
	v_mov_b32_e32 v213, v215
	v_mov_b32_e32 v214, v191
	v_mov_b32_e32 v215, v192
	v_mov_b32_e32 v191, v193
	v_mov_b32_e32 v192, v217
	v_mov_b32_e32 v193, v218
	v_mov_b32_e32 v217, v219
	v_mov_b32_e32 v218, v221
	v_mov_b32_e32 v219, v222
	v_mov_b32_e32 v221, v223
	v_mov_b32_e32 v222, v81
	v_mov_b32_e32 v223, v82
	v_mov_b32_e32 v81, v83
	v_mov_b32_e32 v82, v85
	v_mov_b32_e32 v83, v86
	v_mov_b32_e32 v85, v87
	v_pk_add_f32 v[86:87], v[194:195], v[208:209]
	v_pk_add_f32 v[186:187], v[210:211], v[186:187]
	v_pk_add_f32 v[188:189], v[188:189], v[212:213]
	v_pk_add_f32 v[192:193], v[192:193], v[216:217]
	v_pk_add_f32 v[80:81], v[222:223], v[80:81]
	v_pk_add_f32 v[82:83], v[82:83], v[84:85]
	v_add_f32_e32 v84, v86, v87
	v_pk_add_f32 v[190:191], v[214:215], v[190:191]
	v_add_f32_e32 v85, v186, v187
	v_add_f32_e32 v86, v188, v189
	v_add_f32_e32 v186, v192, v193
	v_add_f32_e32 v80, v80, v81
	v_add_f32_e32 v81, v82, v83
	ds_bpermute_b32 v82, v205, v84
	v_add_f32_e32 v87, v190, v191
	ds_bpermute_b32 v188, v205, v86
	ds_bpermute_b32 v190, v205, v186
	v_pk_add_f32 v[194:195], v[218:219], v[220:221]
	ds_bpermute_b32 v83, v205, v85
	v_add_f32_e32 v187, v194, v195
	ds_bpermute_b32 v192, v205, v80
	s_waitcnt lgkmcnt(4)
	v_add_f32_e32 v82, v84, v82
	ds_bpermute_b32 v189, v205, v87
	ds_bpermute_b32 v191, v205, v187
	ds_bpermute_b32 v193, v205, v81
	s_waitcnt lgkmcnt(6)
	v_add_f32_e32 v84, v86, v188
	s_waitcnt lgkmcnt(5)
	v_add_f32_e32 v86, v186, v190
	ds_bpermute_b32 v186, v206, v82
	s_waitcnt lgkmcnt(5)
	v_add_f32_e32 v83, v85, v83
	s_waitcnt lgkmcnt(4)
	v_add_f32_e32 v80, v80, v192
	s_waitcnt lgkmcnt(3)
	v_add_f32_e32 v85, v87, v189
	s_waitcnt lgkmcnt(2)
	v_add_f32_e32 v87, v187, v191
	s_waitcnt lgkmcnt(1)
	v_add_f32_e32 v81, v81, v193
	ds_bpermute_b32 v187, v206, v83
	ds_bpermute_b32 v188, v206, v84
	ds_bpermute_b32 v193, v206, v80
	s_waitcnt lgkmcnt(3)
	v_add_f32_e32 v82, v82, v186
	v_fmamk_f32 v82, v82, 0x3a800000, v204
	ds_bpermute_b32 v190, v206, v86
	v_rsq_f32_e32 v186, v82
	ds_bpermute_b32 v82, v206, v81
	s_waitcnt lgkmcnt(4)
	v_add_f32_e32 v83, v83, v187
	s_waitcnt lgkmcnt(3)
	v_add_f32_e32 v84, v84, v188
	s_waitcnt lgkmcnt(2)
	v_add_f32_e32 v80, v80, v193
	v_fmamk_f32 v83, v83, 0x3a800000, v204
	v_fmamk_f32 v84, v84, 0x3a800000, v204
	v_fmamk_f32 v80, v80, 0x3a800000, v204
	ds_bpermute_b32 v189, v206, v85
	s_waitcnt lgkmcnt(2)
	v_add_f32_e32 v86, v86, v190
	v_rsq_f32_e32 v188, v83
	v_rsq_f32_e32 v190, v84
	v_rsq_f32_e32 v84, v80
	s_waitcnt lgkmcnt(1)
	v_add_f32_e32 v80, v81, v82
	v_pk_mul_f32 v[82:83], v[124:125], v[186:187] op_sel_hi:[1,0]
	v_pk_mul_f32 v[124:125], v[126:127], v[186:187] op_sel_hi:[1,0]
	ds_bpermute_b32 v191, v206, v87
	v_pk_mul_f32 v[126:127], v[14:15], v[124:125]
	v_pk_mul_f32 v[124:125], v[12:13], v[82:83]
	v_lshlrev_b64 v[82:83], 12, v[176:177]
	v_lshl_add_u64 v[176:177], s[70:71], 0, v[82:83]
	v_lshlrev_b64 v[82:83], 2, v[174:175]
	v_pk_mul_f32 v[112:113], v[112:113], v[186:187] op_sel_hi:[1,0]
	v_pk_mul_f32 v[114:115], v[114:115], v[186:187] op_sel_hi:[1,0]
	v_lshl_add_u64 v[174:175], v[176:177], 0, v[82:83]
	v_pk_mul_f32 v[114:115], v[2:3], v[114:115]
	v_pk_mul_f32 v[112:113], v[0:1], v[112:113]
	global_store_dwordx4 v[174:175], v[112:115], off offset:528
	s_waitcnt lgkmcnt(1)
	v_pk_mul_f32 v[96:97], v[96:97], v[188:189] op_sel_hi:[1,0]
	v_pk_mul_f32 v[98:99], v[98:99], v[188:189] op_sel_hi:[1,0]
	v_lshlrev_b64 v[112:113], 12, v[172:173]
	v_lshl_add_u64 v[112:113], s[70:71], 0, v[112:113]
	v_lshl_add_u64 v[112:113], v[112:113], 0, v[82:83]
	v_pk_mul_f32 v[98:99], v[2:3], v[98:99]
	v_pk_mul_f32 v[96:97], v[0:1], v[96:97]
	global_store_dwordx4 v[112:113], v[96:99], off offset:528
	s_waitcnt lgkmcnt(0)
;     __device__ __forceinline__ void operator()(const f32x4 (&acc)[2][2][4][2], const Unit& u, int wr, int wc, int fr, int fq) const {
;     ...
; #pragma unroll
;         for (int ai = 0; ai < 2; ++ai)
; #pragma unroll
;             for (int m = 0; m < 4; ++m) { const size_t off = (size_t)(row0 + ai * HALF + m * 16) * D_MODEL + col0; const float r = rs[ai][m];
; #pragma unroll
;                 for (int bj = 0; bj < 2; ++bj) { *(f32x4*)(out + off + bj * HALF) = o[ai][m][bj][0] * r * gv[bj][0]; *(f32x4*)(out + off + bj * HALF + 4) = o[ai][m][bj][1] * r * gv[bj][1]; } }
	v_pk_mul_f32 v[94:95], v[94:95], v[190:191] op_sel_hi:[1,0]
	v_add_f32_e32 v85, v85, v189
	v_pk_mul_f32 v[98:99], v[144:145], v[190:191] op_sel_hi:[1,0]
	v_pk_mul_f32 v[96:97], v[14:15], v[94:95]
	v_pk_mul_f32 v[94:95], v[12:13], v[98:99]
	v_lshlrev_b64 v[98:99], 12, v[170:171]
	v_lshl_add_u64 v[98:99], s[70:71], 0, v[98:99]
	v_lshl_add_u64 v[98:99], v[98:99], 0, v[82:83]
	global_store_dwordx4 v[98:99], v[94:97], off
	v_pk_mul_f32 v[90:91], v[90:91], v[190:191] op_sel_hi:[1,0]
	v_fmamk_f32 v85, v85, 0x3a800000, v204
	v_pk_mul_f32 v[94:95], v[140:141], v[190:191] op_sel_hi:[1,0]
	v_pk_mul_f32 v[96:97], v[10:11], v[90:91]
	v_pk_mul_f32 v[94:95], v[8:9], v[94:95]
	v_rsq_f32_e32 v192, v85
	global_store_dwordx4 v[98:99], v[94:97], off offset:16
	v_pk_mul_f32 v[90:91], v[142:143], v[190:191] op_sel_hi:[1,0]
	v_fmamk_f32 v86, v86, 0x3a800000, v204
	v_pk_mul_f32 v[94:95], v[136:137], v[190:191] op_sel_hi:[1,0]
	v_rsq_f32_e32 v194, v86
	v_pk_mul_f32 v[96:97], v[6:7], v[94:95]
	v_pk_mul_f32 v[94:95], v[4:5], v[90:91]
	global_store_dwordx4 v[98:99], v[94:97], off offset:512
	v_pk_mul_f32 v[90:91], v[146:147], v[190:191] op_sel_hi:[1,0]
	v_add_f32_e32 v87, v87, v191
	v_pk_mul_f32 v[94:95], v[138:139], v[190:191] op_sel_hi:[1,0]
	v_fmamk_f32 v87, v87, 0x3a800000, v204
	v_pk_mul_f32 v[96:97], v[2:3], v[94:95]
	v_pk_mul_f32 v[94:95], v[0:1], v[90:91]
	global_store_dwordx4 v[98:99], v[94:97], off offset:528
	v_pk_mul_f32 v[90:91], v[150:151], v[192:193] op_sel_hi:[1,0]
	v_rsq_f32_e32 v86, v87
	v_pk_mul_f32 v[94:95], v[148:149], v[192:193] op_sel_hi:[1,0]
	v_pk_mul_f32 v[48:49], v[48:49], v[194:195] op_sel_hi:[1,0]
	v_pk_mul_f32 v[96:97], v[14:15], v[94:95]
	v_pk_mul_f32 v[94:95], v[12:13], v[90:91]
	v_lshlrev_b64 v[90:91], 12, v[168:169]
	v_lshl_add_u64 v[90:91], s[70:71], 0, v[90:91]
	v_lshl_add_u64 v[90:91], v[90:91], 0, v[82:83]
	global_store_dwordx4 v[90:91], v[94:97], off
	v_pk_mul_f32 v[50:51], v[50:51], v[194:195] op_sel_hi:[1,0]
	v_pk_mul_f32 v[48:49], v[0:1], v[48:49]
	v_pk_mul_f32 v[94:95], v[134:135], v[192:193] op_sel_hi:[1,0]
	v_pk_mul_f32 v[96:97], v[132:133], v[192:193] op_sel_hi:[1,0]
	v_pk_mul_f32 v[94:95], v[8:9], v[94:95]
	v_pk_mul_f32 v[96:97], v[10:11], v[96:97]
	global_store_dwordx4 v[90:91], v[94:97], off offset:16
	v_pk_mul_f32 v[50:51], v[2:3], v[50:51]
	v_fmamk_f32 v80, v80, 0x3a800000, v204
	v_pk_mul_f32 v[94:95], v[180:181], v[192:193] op_sel_hi:[1,0]
	v_pk_mul_f32 v[96:97], v[178:179], v[192:193] op_sel_hi:[1,0]
	v_pk_mul_f32 v[94:95], v[4:5], v[94:95]
	v_pk_mul_f32 v[96:97], v[6:7], v[96:97]
	global_store_dwordx4 v[90:91], v[94:97], off offset:512
	v_pk_mul_f32 v[32:33], v[32:33], v[86:87] op_sel_hi:[1,0]
	v_pk_mul_f32 v[34:35], v[34:35], v[86:87] op_sel_hi:[1,0]
	v_pk_mul_f32 v[94:95], v[182:183], v[192:193] op_sel_hi:[1,0]
	v_pk_mul_f32 v[96:97], v[130:131], v[192:193] op_sel_hi:[1,0]
	v_pk_mul_f32 v[94:95], v[0:1], v[94:95]
	v_pk_mul_f32 v[96:97], v[2:3], v[96:97]
	global_store_dwordx4 v[90:91], v[94:97], off offset:528
	v_lshlrev_b64 v[90:91], 12, v[184:185]
	v_lshl_add_u64 v[90:91], s[70:71], 0, v[90:91]
	v_lshl_add_u64 v[90:91], v[90:91], 0, v[82:83]
	global_store_dwordx4 v[90:91], v[48:51], off offset:528
	v_rsq_f32_e32 v80, v80
	v_pk_mul_f32 v[34:35], v[2:3], v[34:35]
	v_lshlrev_b64 v[48:49], 12, v[128:129]
	v_lshl_add_u64 v[48:49], s[70:71], 0, v[48:49]
	v_lshl_add_u64 v[48:49], v[48:49], 0, v[82:83]
	v_pk_mul_f32 v[32:33], v[0:1], v[32:33]
	global_store_dwordx4 v[48:49], v[32:35], off offset:528
	v_pk_mul_f32 v[16:17], v[16:17], v[84:85] op_sel_hi:[1,0]
	v_pk_mul_f32 v[18:19], v[18:19], v[84:85] op_sel_hi:[1,0]
	v_lshlrev_b64 v[32:33], 12, v[92:93]
	v_lshl_add_u64 v[32:33], s[70:71], 0, v[32:33]
	v_lshl_add_u64 v[32:33], v[32:33], 0, v[82:83]
	v_pk_mul_f32 v[18:19], v[2:3], v[18:19]
	v_pk_mul_f32 v[16:17], v[0:1], v[16:17]
	v_pk_mul_f32 v[108:109], v[108:109], v[188:189] op_sel_hi:[1,0]
	v_pk_mul_f32 v[60:61], v[60:61], v[194:195] op_sel_hi:[1,0]
	v_pk_mul_f32 v[44:45], v[44:45], v[86:87] op_sel_hi:[1,0]
	v_pk_mul_f32 v[28:29], v[28:29], v[84:85] op_sel_hi:[1,0]
	global_store_dwordx4 v[32:33], v[16:19], off offset:528
	v_pk_mul_f32 v[108:109], v[12:13], v[108:109]
	v_pk_mul_f32 v[60:61], v[12:13], v[60:61]
	v_pk_mul_f32 v[16:17], v[74:75], v[80:81] op_sel_hi:[1,0]
	v_pk_mul_f32 v[44:45], v[12:13], v[44:45]
	v_pk_mul_f32 v[28:29], v[12:13], v[28:29]
	v_pk_mul_f32 v[12:13], v[12:13], v[16:17]
	v_lshlrev_b64 v[16:17], 12, v[88:89]
; #define PG8_BAR __builtin_amdgcn_s_barrier()
;     __device__ __forceinline__ void operator()(const f32x4 (&acc)[2][2][4][2], const Unit& u, int wr, int wc, int fr, int fq) const {
;     ...
; #pragma unroll
;         for (int ai = 0; ai < 2; ++ai)
; #pragma unroll
;             for (int m = 0; m < 4; ++m) { const size_t off = (size_t)(row0 + ai * HALF + m * 16) * D_MODEL + col0; const float r = rs[ai][m];
; #pragma unroll
;                 for (int bj = 0; bj < 2; ++bj) { *(f32x4*)(out + off + bj * HALF) = o[ai][m][bj][0] * r * gv[bj][0]; *(f32x4*)(out + off + bj * HALF + 4) = o[ai][m][bj][1] * r * gv[bj][1]; } }
; template <class Epi>
; __device__ __forceinline__ void gemm_phase(LAS unsigned char* lds, const Gemm g, const StaticOrder& S, const Epi& E) {
;     ...
;         if (!has_next) break;
; #pragma unroll
;         for (int a = 0; a < 2; ++a)
; #pragma unroll
;             for (int b = 0; b < 2; ++b)
; #pragma unroll
;                 for (int m = 0; m < 4; ++m)
; #pragma unroll
;                     for (int n = 0; n < 2; ++n) acc[a][b][m][n] = (f32x4){0.f, 0.f, 0.f, 0.f};
;         cur = nxt; cA = nA; cB = nB; ++ui;
;         if (wr == 1) PG8_BAR;
;     }
	v_pk_mul_f32 v[110:111], v[110:111], v[188:189] op_sel_hi:[1,0]
	v_pk_mul_f32 v[62:63], v[62:63], v[194:195] op_sel_hi:[1,0]
	v_pk_mul_f32 v[46:47], v[46:47], v[86:87] op_sel_hi:[1,0]
	v_pk_mul_f32 v[30:31], v[30:31], v[84:85] op_sel_hi:[1,0]
	v_pk_mul_f32 v[18:19], v[72:73], v[80:81] op_sel_hi:[1,0]
	v_lshl_add_u64 v[16:17], s[70:71], 0, v[16:17]
	v_pk_mul_f32 v[110:111], v[14:15], v[110:111]
	v_pk_mul_f32 v[62:63], v[14:15], v[62:63]
	v_pk_mul_f32 v[46:47], v[14:15], v[46:47]
	v_pk_mul_f32 v[30:31], v[14:15], v[30:31]
	v_pk_mul_f32 v[14:15], v[14:15], v[18:19]
	v_lshl_add_u64 v[16:17], v[16:17], 0, v[82:83]
	global_store_dwordx4 v[174:175], v[124:127], off
	v_pk_mul_f32 v[120:121], v[120:121], v[186:187] op_sel_hi:[1,0]
	v_pk_mul_f32 v[122:123], v[122:123], v[186:187] op_sel_hi:[1,0]
	global_store_dwordx4 v[112:113], v[108:111], off
	v_pk_mul_f32 v[104:105], v[104:105], v[188:189] op_sel_hi:[1,0]
	v_pk_mul_f32 v[106:107], v[106:107], v[188:189] op_sel_hi:[1,0]
	global_store_dwordx4 v[90:91], v[60:63], off
	v_pk_mul_f32 v[56:57], v[56:57], v[194:195] op_sel_hi:[1,0]
	v_pk_mul_f32 v[58:59], v[58:59], v[194:195] op_sel_hi:[1,0]
	global_store_dwordx4 v[48:49], v[44:47], off
	v_pk_mul_f32 v[40:41], v[40:41], v[86:87] op_sel_hi:[1,0]
	v_pk_mul_f32 v[42:43], v[42:43], v[86:87] op_sel_hi:[1,0]
	global_store_dwordx4 v[32:33], v[28:31], off
	v_pk_mul_f32 v[24:25], v[24:25], v[84:85] op_sel_hi:[1,0]
	v_pk_mul_f32 v[26:27], v[26:27], v[84:85] op_sel_hi:[1,0]
	global_store_dwordx4 v[16:17], v[12:15], off
	v_pk_mul_f32 v[122:123], v[10:11], v[122:123]
	v_pk_mul_f32 v[120:121], v[8:9], v[120:121]
	v_pk_mul_f32 v[12:13], v[70:71], v[80:81] op_sel_hi:[1,0]
	v_pk_mul_f32 v[14:15], v[68:69], v[80:81] op_sel_hi:[1,0]
	v_pk_mul_f32 v[106:107], v[10:11], v[106:107]
	v_pk_mul_f32 v[104:105], v[8:9], v[104:105]
	v_pk_mul_f32 v[58:59], v[10:11], v[58:59]
	v_pk_mul_f32 v[56:57], v[8:9], v[56:57]
	v_pk_mul_f32 v[42:43], v[10:11], v[42:43]
	v_pk_mul_f32 v[40:41], v[8:9], v[40:41]
	v_pk_mul_f32 v[26:27], v[10:11], v[26:27]
	v_pk_mul_f32 v[24:25], v[8:9], v[24:25]
	v_pk_mul_f32 v[10:11], v[10:11], v[14:15]
	v_pk_mul_f32 v[8:9], v[8:9], v[12:13]
	global_store_dwordx4 v[174:175], v[120:123], off offset:16
	v_pk_mul_f32 v[116:117], v[116:117], v[186:187] op_sel_hi:[1,0]
	v_pk_mul_f32 v[118:119], v[118:119], v[186:187] op_sel_hi:[1,0]
	global_store_dwordx4 v[112:113], v[104:107], off offset:16
	v_pk_mul_f32 v[100:101], v[100:101], v[188:189] op_sel_hi:[1,0]
	v_pk_mul_f32 v[102:103], v[102:103], v[188:189] op_sel_hi:[1,0]
	global_store_dwordx4 v[90:91], v[56:59], off offset:16
	v_pk_mul_f32 v[52:53], v[52:53], v[194:195] op_sel_hi:[1,0]
	v_pk_mul_f32 v[54:55], v[54:55], v[194:195] op_sel_hi:[1,0]
	global_store_dwordx4 v[48:49], v[40:43], off offset:16
	v_pk_mul_f32 v[36:37], v[36:37], v[86:87] op_sel_hi:[1,0]
	v_pk_mul_f32 v[38:39], v[38:39], v[86:87] op_sel_hi:[1,0]
	global_store_dwordx4 v[32:33], v[24:27], off offset:16
	v_pk_mul_f32 v[20:21], v[20:21], v[84:85] op_sel_hi:[1,0]
	v_pk_mul_f32 v[22:23], v[22:23], v[84:85] op_sel_hi:[1,0]
	global_store_dwordx4 v[16:17], v[8:11], off offset:16
	v_pk_mul_f32 v[118:119], v[6:7], v[118:119]
	v_pk_mul_f32 v[116:117], v[4:5], v[116:117]
	v_pk_mul_f32 v[8:9], v[76:77], v[80:81] op_sel_hi:[1,0]
	v_pk_mul_f32 v[10:11], v[64:65], v[80:81] op_sel_hi:[1,0]
	v_pk_mul_f32 v[102:103], v[6:7], v[102:103]
	v_pk_mul_f32 v[100:101], v[4:5], v[100:101]
	v_pk_mul_f32 v[54:55], v[6:7], v[54:55]
	v_pk_mul_f32 v[52:53], v[4:5], v[52:53]
	v_pk_mul_f32 v[38:39], v[6:7], v[38:39]
	v_pk_mul_f32 v[36:37], v[4:5], v[36:37]
	v_pk_mul_f32 v[22:23], v[6:7], v[22:23]
	v_pk_mul_f32 v[20:21], v[4:5], v[20:21]
	v_pk_mul_f32 v[6:7], v[6:7], v[10:11]
	v_pk_mul_f32 v[4:5], v[4:5], v[8:9]
	global_store_dwordx4 v[174:175], v[116:119], off offset:512
	global_store_dwordx4 v[112:113], v[100:103], off offset:512
	global_store_dwordx4 v[90:91], v[52:55], off offset:512
	global_store_dwordx4 v[48:49], v[36:39], off offset:512
	global_store_dwordx4 v[32:33], v[20:23], off offset:512
	global_store_dwordx4 v[16:17], v[4:7], off offset:512
	s_nop 1
	v_pk_mul_f32 v[4:5], v[78:79], v[80:81] op_sel_hi:[1,0]
	v_pk_mul_f32 v[6:7], v[66:67], v[80:81] op_sel_hi:[1,0]
	v_pk_mul_f32 v[0:1], v[0:1], v[4:5]
	v_pk_mul_f32 v[2:3], v[2:3], v[6:7]
	global_store_dwordx4 v[16:17], v[0:3], off offset:528
	s_cbranch_vccnz .LBB0_1165
	s_andn2_b64 vcc, exec, s[12:13]
	s_cbranch_vccnz .LBB0_1164
	s_barrier
	s_branch .LBB0_1164
